# k22: k17 + barrier between chunk-state GEMM and carry chain removed; sample GLU between carry chain and attention queue behind an acquire on a release counter; ticket atomic not waited at issue
# baseline (speedup 1.0000x reference)
; #define LAS __attribute__((address_space(3)))
; __global__ void __launch_bounds__(NTHR, 2) hymba_fwd(Params P) {
;     ...
;     for (int it = blk; it < 128; it += G) {
;         const int mb = it & 15, ns = it >> 4;
;         LAS float* Cs = (LAS float*)lds; constexpr int ldc = 68;
;         __syncthreads();
;         skinny32(Cs, YSS + (size_t)(32 * mb) * SW, SW, WGLU, SW, 64, SW, [&](int ct) { return 64 * ns + 16 * ct; });
.Lmy_glu_pre:
	s_cmpk_gt_i32 s2, 0x7f
	s_cbranch_scc1 .Lmy_glu_skip
	s_mov_b32 s5, 0

; #define LAS __attribute__((address_space(3)))
; #define TIDS() const int tid = fresh_tid(), lane = tid & 63, wave = __builtin_amdgcn_readfirstlane(tid >> 6); (void)lane; (void)wave
; #define CTL WSP(unsigned, WS_CTL)
; __global__ void __launch_bounds__(NTHR, 2) hymba_fwd(Params P) {
;     ...
;     for (int rep = 0; rep < REP_ATT; ++rep) {
;         TIDS();
;         float gqm = fabsf(P.q_g[lane]), gkm = fabsf(P.k_g[lane]);
; #pragma unroll
;         for (int o = 1; o < 64; o <<= 1) { gqm = fmaxf(gqm, __shfl_xor(gqm, o)); gkm = fmaxf(gkm, __shfl_xor(gkm, o)); }
;         const float qkmax = 64.f * gqm * gkm * C2 * 1.02f + 0.25f, thresh = 37.f + 2.f * qkmax;
;         LAS unsigned* uw = (LAS unsigned*)(lds + att::LDS_UNIT);
;         constexpr int NUNITS = 64 + NB * NH * (SEQ / 256);
;         unsigned nxt_ui = 0u;
;         if (tid == 0) nxt_ui = atomicAdd(CTL + 64 + 64 * rep, 1u);
.Lmy_glu_end:
.Lmy_glu_skip:
.LBB0_713:
	v_mov_b32_e32 v4, v208
	v_mbcnt_hi_u32_b32 v2, -1, v202
	v_and_b32_e32 v0, 63, v4
	v_lshlrev_b32_e32 v0, 2, v0
	global_load_dword v1, v0, s[64:65]
	s_nop 0
	global_load_dword v0, v0, s[66:67]
	v_and_b32_e32 v128, 64, v2
	v_xor_b32_e32 v3, 1, v2
	v_add_u32_e32 v10, 64, v128
	v_cmp_lt_i32_e32 vcc, v3, v10
	v_xor_b32_e32 v5, 2, v2
	v_xor_b32_e32 v6, 4, v2
	v_cndmask_b32_e32 v3, v2, v3, vcc
	v_lshlrev_b32_e32 v3, 2, v3
	v_cmp_lt_i32_e32 vcc, v5, v10
	v_xor_b32_e32 v7, 8, v2
	v_xor_b32_e32 v8, 16, v2
	v_cndmask_b32_e32 v5, v2, v5, vcc
	v_lshlrev_b32_e32 v5, 2, v5
	v_cmp_lt_i32_e32 vcc, v6, v10
	v_xor_b32_e32 v9, 32, v2
	v_mov_b32_e32 v129, 0
	v_cndmask_b32_e32 v6, v2, v6, vcc
	v_lshlrev_b32_e32 v6, 2, v6
	v_cmp_lt_i32_e32 vcc, v7, v10
	v_cmp_eq_u32_e64 s[4:5], 0, v4
	s_waitcnt vmcnt(1)
	v_and_b32_e32 v11, 0x7fffffff, v1
	s_waitcnt vmcnt(0)
	v_and_b32_e32 v12, 0x7fffffff, v0
	ds_bpermute_b32 v11, v3, v11
	ds_bpermute_b32 v3, v3, v12
	v_max_f32_e64 v1, |v1|, |v1|
	v_max_f32_e64 v0, |v0|, |v0|
	s_waitcnt lgkmcnt(1)
	v_max_f32_e32 v11, v11, v11
	s_waitcnt lgkmcnt(0)
	v_max_f32_e32 v3, v3, v3
	v_max_f32_e32 v1, v1, v11
	v_max_f32_e32 v0, v0, v3
	ds_bpermute_b32 v3, v5, v1
	ds_bpermute_b32 v5, v5, v0
	s_waitcnt lgkmcnt(1)
	v_max_f32_e32 v3, v3, v3
	s_waitcnt lgkmcnt(0)
	v_max_f32_e32 v5, v5, v5
	v_max_f32_e32 v1, v1, v3
	v_max_f32_e32 v0, v0, v5
	ds_bpermute_b32 v3, v6, v1
	ds_bpermute_b32 v5, v6, v0
	v_cndmask_b32_e32 v6, v2, v7, vcc
	v_lshlrev_b32_e32 v6, 2, v6
	v_cmp_lt_i32_e32 vcc, v8, v10
	s_waitcnt lgkmcnt(1)
	v_max_f32_e32 v3, v3, v3
	s_waitcnt lgkmcnt(0)
	v_max_f32_e32 v5, v5, v5
	v_max_f32_e32 v1, v1, v3
	v_max_f32_e32 v0, v0, v5
	ds_bpermute_b32 v3, v6, v1
	ds_bpermute_b32 v5, v6, v0
	v_cndmask_b32_e32 v6, v2, v8, vcc
	v_lshlrev_b32_e32 v6, 2, v6
	v_cmp_lt_i32_e32 vcc, v9, v10
	s_waitcnt lgkmcnt(1)
	v_max_f32_e32 v3, v3, v3
	s_waitcnt lgkmcnt(0)
	v_max_f32_e32 v5, v5, v5
	v_max_f32_e32 v1, v1, v3
	v_max_f32_e32 v0, v0, v5
	ds_bpermute_b32 v3, v6, v1
	ds_bpermute_b32 v5, v6, v0
	v_cndmask_b32_e32 v2, v2, v9, vcc
	v_lshlrev_b32_e32 v2, 2, v2
	s_waitcnt lgkmcnt(1)
	v_max_f32_e32 v3, v3, v3
	s_waitcnt lgkmcnt(0)
	v_max_f32_e32 v5, v5, v5
	v_max_f32_e32 v1, v1, v3
	v_max_f32_e32 v0, v0, v5
	ds_bpermute_b32 v3, v2, v1
	ds_bpermute_b32 v2, v2, v0
	s_and_saveexec_b64 s[6:7], s[4:5]
	s_cbranch_execz .LBB0_717
	s_mov_b64 s[10:11], exec
	v_mbcnt_lo_u32_b32 v4, s10, 0
	v_mbcnt_hi_u32_b32 v4, s11, v4
	v_cmp_eq_u32_e32 vcc, 0, v4
	s_and_saveexec_b64 s[8:9], vcc
	s_cbranch_execz .LBB0_716
	s_bcnt1_i32_b64 s10, s[10:11]
	v_mov_b32_e32 v5, 0
	v_mov_b32_e32 v6, s10
	global_atomic_add v5, v5, v6, s[92:93] offset:256 sc0
